# weighted-v token loop regenerated: rows reloaded in place, per-round counted waits, no end-of-iteration drain
# speedup vs baseline: 1.0075x; 1.0029x over previous
; DI void eseg_load(ESeg& r, __amdgpu_buffer_rsrc_t rs, int voff) { r.a = __builtin_amdgcn_raw_buffer_load_b128(rs, voff, 0, 0); r.b = __builtin_amdgcn_raw_buffer_load_b64(rs, voff + 16, 0, 0); }
; DI v32f eseg_unpack(const ESeg& r) { return __builtin_amdgcn_cvt_scalef32_pk32_f32_fp6((v6i){(int)r.a.x, (int)r.a.y, (int)r.a.z, (int)r.a.w, (int)r.b.x, (int)r.b.y}, 1.0f); }
; DI int id_of(const u32x4 (&d)[2], int r, unsigned mask = 0xffffu) { const unsigned w = d[r >> 3][(r >> 1) & 3]; return (r & 1) ? (int)((w >> 16) & mask) : (int)(w & mask); }
;     ...
;     for (;;) {
;         const int tn = t + nwx, tnn = tn + nwx, tn_c = tn < nrows ? tn : t, tnn_c = tnn < nrows ? tnn : t;
;         ids_load(idnn, RI16, tnn_c, g);
;         float wt[16];
; #pragma unroll
;         for (int q = 0; q < 4; ++q) { wt[q * 4] = wq[q].x; wt[q * 4 + 1] = wq[q].y; wt[q * 4 + 2] = wq[q].z; wt[q * 4 + 3] = wq[q].w; }
; #pragma unroll
;         for (int q = 0; q < 16; ++q) asm volatile("" : "+v"(wt[q]));
;         __builtin_amdgcn_sched_barrier(0);
; #pragma unroll
;         for (int q = 0; q < 4; ++q) wq[q] = *(const f32x4*)(Wg + (size_t)tn_c * 128 + q * 4);
;         float* xp = F.X + (size_t)t * D + col;
;         const f32x4 x1 = *(const f32x4*)xp, g2 = *(const f32x4*)(F.mod + ((size_t)l * 9 + modrow(t)) * MODW + 5 * D + col);
;         __builtin_amdgcn_sched_barrier(0);
;         f32x2 fa[16];
; #pragma unroll
;         for (int j = 0; j < 16; ++j) fa[j] = (f32x2){0.f, 0.f};
; #pragma unroll
;         for (int r = 0; r < 16; ++r) {
;             const v32f rr = eseg_unpack(rw[r]); const f32x2 w2 = {wt[r], wt[r]};
; #pragma unroll
;             for (int j = 0; j < 16; ++j) fa[j] = __builtin_elementwise_fma((f32x2){rr[2 * j], rr[2 * j + 1]}, w2, fa[j]);
;             eseg_load(rw[r], VS, id_of(idn, r, mask) * ESEG + s24);
;             if (r & 1) __builtin_amdgcn_sched_barrier(0);
;         }
.LBB0_1095:
	v_add_u32_e32 v1, s3, v0
	v_cmp_gt_i32_e64 s[0:1], s15, v1
	v_add_u32_e32 v250, s2, v0
	v_cmp_le_i32_e64 s[36:37], s15, v250
	v_cndmask_b32_e64 v2, v0, v1, s[0:1]
	v_ashrrev_i32_e32 v3, 31, v2
	v_lshlrev_b64 v[2:3], 8, v[2:3]
	v_lshl_add_u64 v[2:3], v[218:219], 0, v[2:3]
	global_load_dwordx4 v[130:133], v[2:3], off offset:16
	global_load_dwordx4 v[134:137], v[2:3], off
	v_cmp_gt_i32_e64 s[0:1], s15, v250
	s_nop 1
	v_cndmask_b32_e64 v2, v0, v250, s[0:1]
	v_ashrrev_i32_e32 v1, 31, v0
	v_lshrrev_b32_e32 v1, 21, v1
	v_add_u32_e32 v1, v0, v1
	v_ashrrev_i32_e32 v1, 11, v1
	v_cmp_gt_i32_e64 s[0:1], s13, v0
	v_ashrrev_i32_e32 v3, 31, v2
	v_lshlrev_b64 v[2:3], 9, v[2:3]
	v_cndmask_b32_e64 v0, 8, v1, s[0:1]
	s_mul_i32 s0, s92, 9
	v_add_u32_e32 v0, s0, v0
	v_lshl_add_u64 v[2:3], v[214:215], 0, v[2:3]
	v_mul_hi_i32_i24_e32 v1, 0xc000, v0
	v_mul_i32_i24_e32 v0, 0xc000, v0
	global_load_dwordx4 v[138:141], v[2:3], off offset:48
	global_load_dwordx4 v[142:145], v[2:3], off offset:32
	global_load_dwordx4 v[146:149], v[2:3], off offset:16
	global_load_dwordx4 v[150:153], v[2:3], off
	global_load_dwordx4 v[166:169], v[220:221], off
	v_lshl_add_u64 v[0:1], s[4:5], 0, v[0:1]
	v_lshl_add_u64 v[0:1], v[216:217], 2, v[0:1]
	s_mov_b32 s0, 0x10a000
	v_add_co_u32_e64 v0, s[0:1], s0, v0
	s_nop 1
	v_addc_co_u32_e64 v1, s[0:1], 0, v1, s[0:1]
	global_load_dwordx4 v[170:173], v[0:1], off
	s_waitcnt vmcnt(39)
	v_cvt_scalef32_pk32_f32_fp6 v[0:31], v[122:127], 1.0
	v_and_b32_e32 v210, 0xffff, v186
	v_mad_u32_u24 v210, v210, s12, v128
	v_pk_fma_f32 v[194:195], v[0:1], v[178:179], 0 op_sel_hi:[1,0,0]
	v_pk_fma_f32 v[196:197], v[2:3], v[178:179], 0 op_sel_hi:[1,0,0]
	v_pk_fma_f32 v[198:199], v[4:5], v[178:179], 0 op_sel_hi:[1,0,0]
	v_pk_fma_f32 v[200:201], v[6:7], v[178:179], 0 op_sel_hi:[1,0,0]
	v_pk_fma_f32 v[202:203], v[8:9], v[178:179], 0 op_sel_hi:[1,0,0]
	v_pk_fma_f32 v[204:205], v[10:11], v[178:179], 0 op_sel_hi:[1,0,0]
	v_pk_fma_f32 v[224:225], v[12:13], v[178:179], 0 op_sel_hi:[1,0,0]
	v_pk_fma_f32 v[226:227], v[14:15], v[178:179], 0 op_sel_hi:[1,0,0]
	v_pk_fma_f32 v[228:229], v[16:17], v[178:179], 0 op_sel_hi:[1,0,0]
	v_pk_fma_f32 v[230:231], v[18:19], v[178:179], 0 op_sel_hi:[1,0,0]
	v_pk_fma_f32 v[232:233], v[20:21], v[178:179], 0 op_sel_hi:[1,0,0]
	v_pk_fma_f32 v[234:235], v[22:23], v[178:179], 0 op_sel_hi:[1,0,0]
	v_pk_fma_f32 v[236:237], v[24:25], v[178:179], 0 op_sel_hi:[1,0,0]
	v_pk_fma_f32 v[182:183], v[26:27], v[178:179], 0 op_sel_hi:[1,0,0]
	v_pk_fma_f32 v[184:185], v[28:29], v[178:179], 0 op_sel_hi:[1,0,0]
	v_pk_fma_f32 v[208:209], v[30:31], v[178:179], 0 op_sel_hi:[1,0,0]
	buffer_load_dwordx4 v[122:125], v210, s[48:51], 0 offen
	buffer_load_dwordx2 v[126:127], v210, s[48:51], 0 offen offset:16
	s_waitcnt vmcnt(39)
	v_cvt_scalef32_pk32_f32_fp6 v[0:31], v[32:37], 1.0
	v_lshrrev_b32_e32 v210, 16, v186
	v_mad_u32_u24 v210, v210, s12, v128
	v_pk_fma_f32 v[194:195], v[0:1], v[178:179], v[194:195] op_sel:[0,1,0] op_sel_hi:[1,1,1]
	v_pk_fma_f32 v[196:197], v[2:3], v[178:179], v[196:197] op_sel:[0,1,0] op_sel_hi:[1,1,1]
	v_pk_fma_f32 v[198:199], v[4:5], v[178:179], v[198:199] op_sel:[0,1,0] op_sel_hi:[1,1,1]
	v_pk_fma_f32 v[200:201], v[6:7], v[178:179], v[200:201] op_sel:[0,1,0] op_sel_hi:[1,1,1]
	v_pk_fma_f32 v[202:203], v[8:9], v[178:179], v[202:203] op_sel:[0,1,0] op_sel_hi:[1,1,1]
	v_pk_fma_f32 v[204:205], v[10:11], v[178:179], v[204:205] op_sel:[0,1,0] op_sel_hi:[1,1,1]
	v_pk_fma_f32 v[224:225], v[12:13], v[178:179], v[224:225] op_sel:[0,1,0] op_sel_hi:[1,1,1]
	v_pk_fma_f32 v[226:227], v[14:15], v[178:179], v[226:227] op_sel:[0,1,0] op_sel_hi:[1,1,1]
	v_pk_fma_f32 v[228:229], v[16:17], v[178:179], v[228:229] op_sel:[0,1,0] op_sel_hi:[1,1,1]
	v_pk_fma_f32 v[230:231], v[18:19], v[178:179], v[230:231] op_sel:[0,1,0] op_sel_hi:[1,1,1]
	v_pk_fma_f32 v[232:233], v[20:21], v[178:179], v[232:233] op_sel:[0,1,0] op_sel_hi:[1,1,1]
	v_pk_fma_f32 v[234:235], v[22:23], v[178:179], v[234:235] op_sel:[0,1,0] op_sel_hi:[1,1,1]
	v_pk_fma_f32 v[236:237], v[24:25], v[178:179], v[236:237] op_sel:[0,1,0] op_sel_hi:[1,1,1]
	v_pk_fma_f32 v[182:183], v[26:27], v[178:179], v[182:183] op_sel:[0,1,0] op_sel_hi:[1,1,1]
	v_pk_fma_f32 v[184:185], v[28:29], v[178:179], v[184:185] op_sel:[0,1,0] op_sel_hi:[1,1,1]
	v_pk_fma_f32 v[208:209], v[30:31], v[178:179], v[208:209] op_sel:[0,1,0] op_sel_hi:[1,1,1]
	buffer_load_dwordx4 v[32:35], v210, s[48:51], 0 offen
	buffer_load_dwordx2 v[36:37], v210, s[48:51], 0 offen offset:16
	s_waitcnt vmcnt(39)
	v_cvt_scalef32_pk32_f32_fp6 v[0:31], v[116:121], 1.0
	v_and_b32_e32 v210, 0xffff, v187
	v_mad_u32_u24 v210, v210, s12, v128
	v_pk_fma_f32 v[194:195], v[0:1], v[180:181], v[194:195] op_sel_hi:[1,0,1]
	v_pk_fma_f32 v[196:197], v[2:3], v[180:181], v[196:197] op_sel_hi:[1,0,1]
	v_pk_fma_f32 v[198:199], v[4:5], v[180:181], v[198:199] op_sel_hi:[1,0,1]
	v_pk_fma_f32 v[200:201], v[6:7], v[180:181], v[200:201] op_sel_hi:[1,0,1]
	v_pk_fma_f32 v[202:203], v[8:9], v[180:181], v[202:203] op_sel_hi:[1,0,1]
	v_pk_fma_f32 v[204:205], v[10:11], v[180:181], v[204:205] op_sel_hi:[1,0,1]
	v_pk_fma_f32 v[224:225], v[12:13], v[180:181], v[224:225] op_sel_hi:[1,0,1]
	v_pk_fma_f32 v[226:227], v[14:15], v[180:181], v[226:227] op_sel_hi:[1,0,1]
	v_pk_fma_f32 v[228:229], v[16:17], v[180:181], v[228:229] op_sel_hi:[1,0,1]
	v_pk_fma_f32 v[230:231], v[18:19], v[180:181], v[230:231] op_sel_hi:[1,0,1]
	v_pk_fma_f32 v[232:233], v[20:21], v[180:181], v[232:233] op_sel_hi:[1,0,1]
	v_pk_fma_f32 v[234:235], v[22:23], v[180:181], v[234:235] op_sel_hi:[1,0,1]
	v_pk_fma_f32 v[236:237], v[24:25], v[180:181], v[236:237] op_sel_hi:[1,0,1]
	v_pk_fma_f32 v[182:183], v[26:27], v[180:181], v[182:183] op_sel_hi:[1,0,1]
	v_pk_fma_f32 v[184:185], v[28:29], v[180:181], v[184:185] op_sel_hi:[1,0,1]
	v_pk_fma_f32 v[208:209], v[30:31], v[180:181], v[208:209] op_sel_hi:[1,0,1]
	buffer_load_dwordx4 v[116:119], v210, s[48:51], 0 offen
	buffer_load_dwordx2 v[120:121], v210, s[48:51], 0 offen offset:16
	s_waitcnt vmcnt(39)
; DI void eseg_load(ESeg& r, __amdgpu_buffer_rsrc_t rs, int voff) { r.a = __builtin_amdgcn_raw_buffer_load_b128(rs, voff, 0, 0); r.b = __builtin_amdgcn_raw_buffer_load_b64(rs, voff + 16, 0, 0); }
; DI v32f eseg_unpack(const ESeg& r) { return __builtin_amdgcn_cvt_scalef32_pk32_f32_fp6((v6i){(int)r.a.x, (int)r.a.y, (int)r.a.z, (int)r.a.w, (int)r.b.x, (int)r.b.y}, 1.0f); }
; DI int id_of(const u32x4 (&d)[2], int r, unsigned mask = 0xffffu) { const unsigned w = d[r >> 3][(r >> 1) & 3]; return (r & 1) ? (int)((w >> 16) & mask) : (int)(w & mask); }
;     ...
; #pragma unroll
;         for (int r = 0; r < 16; ++r) {
;             const v32f rr = eseg_unpack(rw[r]); const f32x2 w2 = {wt[r], wt[r]};
; #pragma unroll
;             for (int j = 0; j < 16; ++j) fa[j] = __builtin_elementwise_fma((f32x2){rr[2 * j], rr[2 * j + 1]}, w2, fa[j]);
;             eseg_load(rw[r], VS, id_of(idn, r, mask) * ESEG + s24);
;             if (r & 1) __builtin_amdgcn_sched_barrier(0);
;         }
	v_cvt_scalef32_pk32_f32_fp6 v[0:31], v[38:43], 1.0
	v_lshrrev_b32_e32 v210, 16, v187
	v_mad_u32_u24 v210, v210, s12, v128
	v_pk_fma_f32 v[194:195], v[0:1], v[180:181], v[194:195] op_sel:[0,1,0] op_sel_hi:[1,1,1]
	v_pk_fma_f32 v[196:197], v[2:3], v[180:181], v[196:197] op_sel:[0,1,0] op_sel_hi:[1,1,1]
	v_pk_fma_f32 v[198:199], v[4:5], v[180:181], v[198:199] op_sel:[0,1,0] op_sel_hi:[1,1,1]
	v_pk_fma_f32 v[200:201], v[6:7], v[180:181], v[200:201] op_sel:[0,1,0] op_sel_hi:[1,1,1]
	v_pk_fma_f32 v[202:203], v[8:9], v[180:181], v[202:203] op_sel:[0,1,0] op_sel_hi:[1,1,1]
	v_pk_fma_f32 v[204:205], v[10:11], v[180:181], v[204:205] op_sel:[0,1,0] op_sel_hi:[1,1,1]
	v_pk_fma_f32 v[224:225], v[12:13], v[180:181], v[224:225] op_sel:[0,1,0] op_sel_hi:[1,1,1]
	v_pk_fma_f32 v[226:227], v[14:15], v[180:181], v[226:227] op_sel:[0,1,0] op_sel_hi:[1,1,1]
	v_pk_fma_f32 v[228:229], v[16:17], v[180:181], v[228:229] op_sel:[0,1,0] op_sel_hi:[1,1,1]
	v_pk_fma_f32 v[230:231], v[18:19], v[180:181], v[230:231] op_sel:[0,1,0] op_sel_hi:[1,1,1]
	v_pk_fma_f32 v[232:233], v[20:21], v[180:181], v[232:233] op_sel:[0,1,0] op_sel_hi:[1,1,1]
	v_pk_fma_f32 v[234:235], v[22:23], v[180:181], v[234:235] op_sel:[0,1,0] op_sel_hi:[1,1,1]
	v_pk_fma_f32 v[236:237], v[24:25], v[180:181], v[236:237] op_sel:[0,1,0] op_sel_hi:[1,1,1]
	v_pk_fma_f32 v[182:183], v[26:27], v[180:181], v[182:183] op_sel:[0,1,0] op_sel_hi:[1,1,1]
	v_pk_fma_f32 v[184:185], v[28:29], v[180:181], v[184:185] op_sel:[0,1,0] op_sel_hi:[1,1,1]
	v_pk_fma_f32 v[208:209], v[30:31], v[180:181], v[208:209] op_sel:[0,1,0] op_sel_hi:[1,1,1]
	buffer_load_dwordx4 v[38:41], v210, s[48:51], 0 offen
	buffer_load_dwordx2 v[42:43], v210, s[48:51], 0 offen offset:16
	s_waitcnt vmcnt(39)
	v_cvt_scalef32_pk32_f32_fp6 v[0:31], v[110:115], 1.0
	v_and_b32_e32 v210, 0xffff, v188
	v_mad_u32_u24 v210, v210, s12, v128
	v_pk_fma_f32 v[194:195], v[0:1], v[190:191], v[194:195] op_sel_hi:[1,0,1]
	v_pk_fma_f32 v[196:197], v[2:3], v[190:191], v[196:197] op_sel_hi:[1,0,1]
	v_pk_fma_f32 v[198:199], v[4:5], v[190:191], v[198:199] op_sel_hi:[1,0,1]
	v_pk_fma_f32 v[200:201], v[6:7], v[190:191], v[200:201] op_sel_hi:[1,0,1]
	v_pk_fma_f32 v[202:203], v[8:9], v[190:191], v[202:203] op_sel_hi:[1,0,1]
	v_pk_fma_f32 v[204:205], v[10:11], v[190:191], v[204:205] op_sel_hi:[1,0,1]
	v_pk_fma_f32 v[224:225], v[12:13], v[190:191], v[224:225] op_sel_hi:[1,0,1]
	v_pk_fma_f32 v[226:227], v[14:15], v[190:191], v[226:227] op_sel_hi:[1,0,1]
	v_pk_fma_f32 v[228:229], v[16:17], v[190:191], v[228:229] op_sel_hi:[1,0,1]
	v_pk_fma_f32 v[230:231], v[18:19], v[190:191], v[230:231] op_sel_hi:[1,0,1]
	v_pk_fma_f32 v[232:233], v[20:21], v[190:191], v[232:233] op_sel_hi:[1,0,1]
	v_pk_fma_f32 v[234:235], v[22:23], v[190:191], v[234:235] op_sel_hi:[1,0,1]
	v_pk_fma_f32 v[236:237], v[24:25], v[190:191], v[236:237] op_sel_hi:[1,0,1]
	v_pk_fma_f32 v[182:183], v[26:27], v[190:191], v[182:183] op_sel_hi:[1,0,1]
	v_pk_fma_f32 v[184:185], v[28:29], v[190:191], v[184:185] op_sel_hi:[1,0,1]
	v_pk_fma_f32 v[208:209], v[30:31], v[190:191], v[208:209] op_sel_hi:[1,0,1]
	buffer_load_dwordx4 v[110:113], v210, s[48:51], 0 offen
	buffer_load_dwordx2 v[114:115], v210, s[48:51], 0 offen offset:16
	s_waitcnt vmcnt(39)
	v_cvt_scalef32_pk32_f32_fp6 v[0:31], v[44:49], 1.0
	v_lshrrev_b32_e32 v210, 16, v188
	v_mad_u32_u24 v210, v210, s12, v128
	v_pk_fma_f32 v[194:195], v[0:1], v[190:191], v[194:195] op_sel:[0,1,0] op_sel_hi:[1,1,1]
	v_pk_fma_f32 v[196:197], v[2:3], v[190:191], v[196:197] op_sel:[0,1,0] op_sel_hi:[1,1,1]
	v_pk_fma_f32 v[198:199], v[4:5], v[190:191], v[198:199] op_sel:[0,1,0] op_sel_hi:[1,1,1]
	v_pk_fma_f32 v[200:201], v[6:7], v[190:191], v[200:201] op_sel:[0,1,0] op_sel_hi:[1,1,1]
	v_pk_fma_f32 v[202:203], v[8:9], v[190:191], v[202:203] op_sel:[0,1,0] op_sel_hi:[1,1,1]
	v_pk_fma_f32 v[204:205], v[10:11], v[190:191], v[204:205] op_sel:[0,1,0] op_sel_hi:[1,1,1]
	v_pk_fma_f32 v[224:225], v[12:13], v[190:191], v[224:225] op_sel:[0,1,0] op_sel_hi:[1,1,1]
	v_pk_fma_f32 v[226:227], v[14:15], v[190:191], v[226:227] op_sel:[0,1,0] op_sel_hi:[1,1,1]
	v_pk_fma_f32 v[228:229], v[16:17], v[190:191], v[228:229] op_sel:[0,1,0] op_sel_hi:[1,1,1]
	v_pk_fma_f32 v[230:231], v[18:19], v[190:191], v[230:231] op_sel:[0,1,0] op_sel_hi:[1,1,1]
	v_pk_fma_f32 v[232:233], v[20:21], v[190:191], v[232:233] op_sel:[0,1,0] op_sel_hi:[1,1,1]
	v_pk_fma_f32 v[234:235], v[22:23], v[190:191], v[234:235] op_sel:[0,1,0] op_sel_hi:[1,1,1]
	v_pk_fma_f32 v[236:237], v[24:25], v[190:191], v[236:237] op_sel:[0,1,0] op_sel_hi:[1,1,1]
	v_pk_fma_f32 v[182:183], v[26:27], v[190:191], v[182:183] op_sel:[0,1,0] op_sel_hi:[1,1,1]
	v_pk_fma_f32 v[184:185], v[28:29], v[190:191], v[184:185] op_sel:[0,1,0] op_sel_hi:[1,1,1]
	v_pk_fma_f32 v[208:209], v[30:31], v[190:191], v[208:209] op_sel:[0,1,0] op_sel_hi:[1,1,1]
	buffer_load_dwordx4 v[44:47], v210, s[48:51], 0 offen
	buffer_load_dwordx2 v[48:49], v210, s[48:51], 0 offen offset:16
	s_waitcnt vmcnt(39)
; DI void eseg_load(ESeg& r, __amdgpu_buffer_rsrc_t rs, int voff) { r.a = __builtin_amdgcn_raw_buffer_load_b128(rs, voff, 0, 0); r.b = __builtin_amdgcn_raw_buffer_load_b64(rs, voff + 16, 0, 0); }
; DI v32f eseg_unpack(const ESeg& r) { return __builtin_amdgcn_cvt_scalef32_pk32_f32_fp6((v6i){(int)r.a.x, (int)r.a.y, (int)r.a.z, (int)r.a.w, (int)r.b.x, (int)r.b.y}, 1.0f); }
; DI int id_of(const u32x4 (&d)[2], int r, unsigned mask = 0xffffu) { const unsigned w = d[r >> 3][(r >> 1) & 3]; return (r & 1) ? (int)((w >> 16) & mask) : (int)(w & mask); }
;     ...
; #pragma unroll
;         for (int r = 0; r < 16; ++r) {
;             const v32f rr = eseg_unpack(rw[r]); const f32x2 w2 = {wt[r], wt[r]};
; #pragma unroll
;             for (int j = 0; j < 16; ++j) fa[j] = __builtin_elementwise_fma((f32x2){rr[2 * j], rr[2 * j + 1]}, w2, fa[j]);
;             eseg_load(rw[r], VS, id_of(idn, r, mask) * ESEG + s24);
;             if (r & 1) __builtin_amdgcn_sched_barrier(0);
;         }
	v_cvt_scalef32_pk32_f32_fp6 v[0:31], v[104:109], 1.0
	v_and_b32_e32 v210, 0xffff, v189
	v_mad_u32_u24 v210, v210, s12, v128
	v_pk_fma_f32 v[194:195], v[0:1], v[192:193], v[194:195] op_sel_hi:[1,0,1]
	v_pk_fma_f32 v[196:197], v[2:3], v[192:193], v[196:197] op_sel_hi:[1,0,1]
	v_pk_fma_f32 v[198:199], v[4:5], v[192:193], v[198:199] op_sel_hi:[1,0,1]
	v_pk_fma_f32 v[200:201], v[6:7], v[192:193], v[200:201] op_sel_hi:[1,0,1]
	v_pk_fma_f32 v[202:203], v[8:9], v[192:193], v[202:203] op_sel_hi:[1,0,1]
	v_pk_fma_f32 v[204:205], v[10:11], v[192:193], v[204:205] op_sel_hi:[1,0,1]
	v_pk_fma_f32 v[224:225], v[12:13], v[192:193], v[224:225] op_sel_hi:[1,0,1]
	v_pk_fma_f32 v[226:227], v[14:15], v[192:193], v[226:227] op_sel_hi:[1,0,1]
	v_pk_fma_f32 v[228:229], v[16:17], v[192:193], v[228:229] op_sel_hi:[1,0,1]
	v_pk_fma_f32 v[230:231], v[18:19], v[192:193], v[230:231] op_sel_hi:[1,0,1]
	v_pk_fma_f32 v[232:233], v[20:21], v[192:193], v[232:233] op_sel_hi:[1,0,1]
	v_pk_fma_f32 v[234:235], v[22:23], v[192:193], v[234:235] op_sel_hi:[1,0,1]
	v_pk_fma_f32 v[236:237], v[24:25], v[192:193], v[236:237] op_sel_hi:[1,0,1]
	v_pk_fma_f32 v[182:183], v[26:27], v[192:193], v[182:183] op_sel_hi:[1,0,1]
	v_pk_fma_f32 v[184:185], v[28:29], v[192:193], v[184:185] op_sel_hi:[1,0,1]
	v_pk_fma_f32 v[208:209], v[30:31], v[192:193], v[208:209] op_sel_hi:[1,0,1]
	buffer_load_dwordx4 v[104:107], v210, s[48:51], 0 offen
	buffer_load_dwordx2 v[108:109], v210, s[48:51], 0 offen offset:16
	s_waitcnt vmcnt(39)
	v_cvt_scalef32_pk32_f32_fp6 v[0:31], v[50:55], 1.0
	v_lshrrev_b32_e32 v210, 16, v189
	v_mad_u32_u24 v210, v210, s12, v128
	v_pk_fma_f32 v[194:195], v[0:1], v[192:193], v[194:195] op_sel:[0,1,0] op_sel_hi:[1,1,1]
	v_pk_fma_f32 v[196:197], v[2:3], v[192:193], v[196:197] op_sel:[0,1,0] op_sel_hi:[1,1,1]
	v_pk_fma_f32 v[198:199], v[4:5], v[192:193], v[198:199] op_sel:[0,1,0] op_sel_hi:[1,1,1]
	v_pk_fma_f32 v[200:201], v[6:7], v[192:193], v[200:201] op_sel:[0,1,0] op_sel_hi:[1,1,1]
	v_pk_fma_f32 v[202:203], v[8:9], v[192:193], v[202:203] op_sel:[0,1,0] op_sel_hi:[1,1,1]
	v_pk_fma_f32 v[204:205], v[10:11], v[192:193], v[204:205] op_sel:[0,1,0] op_sel_hi:[1,1,1]
	v_pk_fma_f32 v[224:225], v[12:13], v[192:193], v[224:225] op_sel:[0,1,0] op_sel_hi:[1,1,1]
	v_pk_fma_f32 v[226:227], v[14:15], v[192:193], v[226:227] op_sel:[0,1,0] op_sel_hi:[1,1,1]
	v_pk_fma_f32 v[228:229], v[16:17], v[192:193], v[228:229] op_sel:[0,1,0] op_sel_hi:[1,1,1]
	v_pk_fma_f32 v[230:231], v[18:19], v[192:193], v[230:231] op_sel:[0,1,0] op_sel_hi:[1,1,1]
	v_pk_fma_f32 v[232:233], v[20:21], v[192:193], v[232:233] op_sel:[0,1,0] op_sel_hi:[1,1,1]
	v_pk_fma_f32 v[234:235], v[22:23], v[192:193], v[234:235] op_sel:[0,1,0] op_sel_hi:[1,1,1]
	v_pk_fma_f32 v[236:237], v[24:25], v[192:193], v[236:237] op_sel:[0,1,0] op_sel_hi:[1,1,1]
	v_pk_fma_f32 v[182:183], v[26:27], v[192:193], v[182:183] op_sel:[0,1,0] op_sel_hi:[1,1,1]
	v_pk_fma_f32 v[184:185], v[28:29], v[192:193], v[184:185] op_sel:[0,1,0] op_sel_hi:[1,1,1]
	v_pk_fma_f32 v[208:209], v[30:31], v[192:193], v[208:209] op_sel:[0,1,0] op_sel_hi:[1,1,1]
	buffer_load_dwordx4 v[50:53], v210, s[48:51], 0 offen
	buffer_load_dwordx2 v[54:55], v210, s[48:51], 0 offen offset:16
	s_waitcnt vmcnt(39)
	v_cvt_scalef32_pk32_f32_fp6 v[0:31], v[98:103], 1.0
	v_and_b32_e32 v210, 0xffff, v158
	v_mad_u32_u24 v210, v210, s12, v128
	v_pk_fma_f32 v[194:195], v[0:1], v[174:175], v[194:195] op_sel_hi:[1,0,1]
	v_pk_fma_f32 v[196:197], v[2:3], v[174:175], v[196:197] op_sel_hi:[1,0,1]
	v_pk_fma_f32 v[198:199], v[4:5], v[174:175], v[198:199] op_sel_hi:[1,0,1]
	v_pk_fma_f32 v[200:201], v[6:7], v[174:175], v[200:201] op_sel_hi:[1,0,1]
	v_pk_fma_f32 v[202:203], v[8:9], v[174:175], v[202:203] op_sel_hi:[1,0,1]
	v_pk_fma_f32 v[204:205], v[10:11], v[174:175], v[204:205] op_sel_hi:[1,0,1]
	v_pk_fma_f32 v[224:225], v[12:13], v[174:175], v[224:225] op_sel_hi:[1,0,1]
	v_pk_fma_f32 v[226:227], v[14:15], v[174:175], v[226:227] op_sel_hi:[1,0,1]
	v_pk_fma_f32 v[228:229], v[16:17], v[174:175], v[228:229] op_sel_hi:[1,0,1]
	v_pk_fma_f32 v[230:231], v[18:19], v[174:175], v[230:231] op_sel_hi:[1,0,1]
	v_pk_fma_f32 v[232:233], v[20:21], v[174:175], v[232:233] op_sel_hi:[1,0,1]
	v_pk_fma_f32 v[234:235], v[22:23], v[174:175], v[234:235] op_sel_hi:[1,0,1]
	v_pk_fma_f32 v[236:237], v[24:25], v[174:175], v[236:237] op_sel_hi:[1,0,1]
	v_pk_fma_f32 v[182:183], v[26:27], v[174:175], v[182:183] op_sel_hi:[1,0,1]
	v_pk_fma_f32 v[184:185], v[28:29], v[174:175], v[184:185] op_sel_hi:[1,0,1]
	v_pk_fma_f32 v[208:209], v[30:31], v[174:175], v[208:209] op_sel_hi:[1,0,1]
	buffer_load_dwordx4 v[98:101], v210, s[48:51], 0 offen
	buffer_load_dwordx2 v[102:103], v210, s[48:51], 0 offen offset:16
	s_waitcnt vmcnt(39)
	v_cvt_scalef32_pk32_f32_fp6 v[0:31], v[56:61], 1.0
	v_lshrrev_b32_e32 v210, 16, v158
	v_mad_u32_u24 v210, v210, s12, v128
	v_pk_fma_f32 v[194:195], v[0:1], v[174:175], v[194:195] op_sel:[0,1,0] op_sel_hi:[1,1,1]
	v_pk_fma_f32 v[196:197], v[2:3], v[174:175], v[196:197] op_sel:[0,1,0] op_sel_hi:[1,1,1]
	v_pk_fma_f32 v[198:199], v[4:5], v[174:175], v[198:199] op_sel:[0,1,0] op_sel_hi:[1,1,1]
	v_pk_fma_f32 v[200:201], v[6:7], v[174:175], v[200:201] op_sel:[0,1,0] op_sel_hi:[1,1,1]
	v_pk_fma_f32 v[202:203], v[8:9], v[174:175], v[202:203] op_sel:[0,1,0] op_sel_hi:[1,1,1]
	v_pk_fma_f32 v[204:205], v[10:11], v[174:175], v[204:205] op_sel:[0,1,0] op_sel_hi:[1,1,1]
	v_pk_fma_f32 v[224:225], v[12:13], v[174:175], v[224:225] op_sel:[0,1,0] op_sel_hi:[1,1,1]
	v_pk_fma_f32 v[226:227], v[14:15], v[174:175], v[226:227] op_sel:[0,1,0] op_sel_hi:[1,1,1]
	v_pk_fma_f32 v[228:229], v[16:17], v[174:175], v[228:229] op_sel:[0,1,0] op_sel_hi:[1,1,1]
	v_pk_fma_f32 v[230:231], v[18:19], v[174:175], v[230:231] op_sel:[0,1,0] op_sel_hi:[1,1,1]
	v_pk_fma_f32 v[232:233], v[20:21], v[174:175], v[232:233] op_sel:[0,1,0] op_sel_hi:[1,1,1]
	v_pk_fma_f32 v[234:235], v[22:23], v[174:175], v[234:235] op_sel:[0,1,0] op_sel_hi:[1,1,1]
	v_pk_fma_f32 v[236:237], v[24:25], v[174:175], v[236:237] op_sel:[0,1,0] op_sel_hi:[1,1,1]
	v_pk_fma_f32 v[182:183], v[26:27], v[174:175], v[182:183] op_sel:[0,1,0] op_sel_hi:[1,1,1]
	v_pk_fma_f32 v[184:185], v[28:29], v[174:175], v[184:185] op_sel:[0,1,0] op_sel_hi:[1,1,1]
	v_pk_fma_f32 v[208:209], v[30:31], v[174:175], v[208:209] op_sel:[0,1,0] op_sel_hi:[1,1,1]
	buffer_load_dwordx4 v[56:59], v210, s[48:51], 0 offen
	buffer_load_dwordx2 v[60:61], v210, s[48:51], 0 offen offset:16
	s_waitcnt vmcnt(39)
; DI void eseg_load(ESeg& r, __amdgpu_buffer_rsrc_t rs, int voff) { r.a = __builtin_amdgcn_raw_buffer_load_b128(rs, voff, 0, 0); r.b = __builtin_amdgcn_raw_buffer_load_b64(rs, voff + 16, 0, 0); }
; DI v32f eseg_unpack(const ESeg& r) { return __builtin_amdgcn_cvt_scalef32_pk32_f32_fp6((v6i){(int)r.a.x, (int)r.a.y, (int)r.a.z, (int)r.a.w, (int)r.b.x, (int)r.b.y}, 1.0f); }
; DI int id_of(const u32x4 (&d)[2], int r, unsigned mask = 0xffffu) { const unsigned w = d[r >> 3][(r >> 1) & 3]; return (r & 1) ? (int)((w >> 16) & mask) : (int)(w & mask); }
;     ...
; #pragma unroll
;         for (int r = 0; r < 16; ++r) {
;             const v32f rr = eseg_unpack(rw[r]); const f32x2 w2 = {wt[r], wt[r]};
; #pragma unroll
;             for (int j = 0; j < 16; ++j) fa[j] = __builtin_elementwise_fma((f32x2){rr[2 * j], rr[2 * j + 1]}, w2, fa[j]);
;             eseg_load(rw[r], VS, id_of(idn, r, mask) * ESEG + s24);
;             if (r & 1) __builtin_amdgcn_sched_barrier(0);
;         }
	v_cvt_scalef32_pk32_f32_fp6 v[0:31], v[92:97], 1.0
	v_and_b32_e32 v210, 0xffff, v159
	v_mad_u32_u24 v210, v210, s12, v128
	v_pk_fma_f32 v[194:195], v[0:1], v[176:177], v[194:195] op_sel_hi:[1,0,1]
	v_pk_fma_f32 v[196:197], v[2:3], v[176:177], v[196:197] op_sel_hi:[1,0,1]
	v_pk_fma_f32 v[198:199], v[4:5], v[176:177], v[198:199] op_sel_hi:[1,0,1]
	v_pk_fma_f32 v[200:201], v[6:7], v[176:177], v[200:201] op_sel_hi:[1,0,1]
	v_pk_fma_f32 v[202:203], v[8:9], v[176:177], v[202:203] op_sel_hi:[1,0,1]
	v_pk_fma_f32 v[204:205], v[10:11], v[176:177], v[204:205] op_sel_hi:[1,0,1]
	v_pk_fma_f32 v[224:225], v[12:13], v[176:177], v[224:225] op_sel_hi:[1,0,1]
	v_pk_fma_f32 v[226:227], v[14:15], v[176:177], v[226:227] op_sel_hi:[1,0,1]
	v_pk_fma_f32 v[228:229], v[16:17], v[176:177], v[228:229] op_sel_hi:[1,0,1]
	v_pk_fma_f32 v[230:231], v[18:19], v[176:177], v[230:231] op_sel_hi:[1,0,1]
	v_pk_fma_f32 v[232:233], v[20:21], v[176:177], v[232:233] op_sel_hi:[1,0,1]
	v_pk_fma_f32 v[234:235], v[22:23], v[176:177], v[234:235] op_sel_hi:[1,0,1]
	v_pk_fma_f32 v[236:237], v[24:25], v[176:177], v[236:237] op_sel_hi:[1,0,1]
	v_pk_fma_f32 v[182:183], v[26:27], v[176:177], v[182:183] op_sel_hi:[1,0,1]
	v_pk_fma_f32 v[184:185], v[28:29], v[176:177], v[184:185] op_sel_hi:[1,0,1]
	v_pk_fma_f32 v[208:209], v[30:31], v[176:177], v[208:209] op_sel_hi:[1,0,1]
	buffer_load_dwordx4 v[92:95], v210, s[48:51], 0 offen
	buffer_load_dwordx2 v[96:97], v210, s[48:51], 0 offen offset:16
	s_waitcnt vmcnt(39)
	v_cvt_scalef32_pk32_f32_fp6 v[0:31], v[62:67], 1.0
	v_lshrrev_b32_e32 v210, 16, v159
	v_mad_u32_u24 v210, v210, s12, v128
	v_pk_fma_f32 v[194:195], v[0:1], v[176:177], v[194:195] op_sel:[0,1,0] op_sel_hi:[1,1,1]
	v_pk_fma_f32 v[196:197], v[2:3], v[176:177], v[196:197] op_sel:[0,1,0] op_sel_hi:[1,1,1]
	v_pk_fma_f32 v[198:199], v[4:5], v[176:177], v[198:199] op_sel:[0,1,0] op_sel_hi:[1,1,1]
	v_pk_fma_f32 v[200:201], v[6:7], v[176:177], v[200:201] op_sel:[0,1,0] op_sel_hi:[1,1,1]
	v_pk_fma_f32 v[202:203], v[8:9], v[176:177], v[202:203] op_sel:[0,1,0] op_sel_hi:[1,1,1]
	v_pk_fma_f32 v[204:205], v[10:11], v[176:177], v[204:205] op_sel:[0,1,0] op_sel_hi:[1,1,1]
	v_pk_fma_f32 v[224:225], v[12:13], v[176:177], v[224:225] op_sel:[0,1,0] op_sel_hi:[1,1,1]
	v_pk_fma_f32 v[226:227], v[14:15], v[176:177], v[226:227] op_sel:[0,1,0] op_sel_hi:[1,1,1]
	v_pk_fma_f32 v[228:229], v[16:17], v[176:177], v[228:229] op_sel:[0,1,0] op_sel_hi:[1,1,1]
	v_pk_fma_f32 v[230:231], v[18:19], v[176:177], v[230:231] op_sel:[0,1,0] op_sel_hi:[1,1,1]
	v_pk_fma_f32 v[232:233], v[20:21], v[176:177], v[232:233] op_sel:[0,1,0] op_sel_hi:[1,1,1]
	v_pk_fma_f32 v[234:235], v[22:23], v[176:177], v[234:235] op_sel:[0,1,0] op_sel_hi:[1,1,1]
	v_pk_fma_f32 v[236:237], v[24:25], v[176:177], v[236:237] op_sel:[0,1,0] op_sel_hi:[1,1,1]
	v_pk_fma_f32 v[182:183], v[26:27], v[176:177], v[182:183] op_sel:[0,1,0] op_sel_hi:[1,1,1]
	v_pk_fma_f32 v[184:185], v[28:29], v[176:177], v[184:185] op_sel:[0,1,0] op_sel_hi:[1,1,1]
	v_pk_fma_f32 v[208:209], v[30:31], v[176:177], v[208:209] op_sel:[0,1,0] op_sel_hi:[1,1,1]
	buffer_load_dwordx4 v[62:65], v210, s[48:51], 0 offen
	buffer_load_dwordx2 v[66:67], v210, s[48:51], 0 offen offset:16
	s_waitcnt vmcnt(39)
	v_cvt_scalef32_pk32_f32_fp6 v[0:31], v[86:91], 1.0
	v_and_b32_e32 v210, 0xffff, v160
	v_mad_u32_u24 v210, v210, s12, v128
	v_pk_fma_f32 v[194:195], v[0:1], v[162:163], v[194:195] op_sel_hi:[1,0,1]
	v_pk_fma_f32 v[196:197], v[2:3], v[162:163], v[196:197] op_sel_hi:[1,0,1]
	v_pk_fma_f32 v[198:199], v[4:5], v[162:163], v[198:199] op_sel_hi:[1,0,1]
	v_pk_fma_f32 v[200:201], v[6:7], v[162:163], v[200:201] op_sel_hi:[1,0,1]
	v_pk_fma_f32 v[202:203], v[8:9], v[162:163], v[202:203] op_sel_hi:[1,0,1]
	v_pk_fma_f32 v[204:205], v[10:11], v[162:163], v[204:205] op_sel_hi:[1,0,1]
	v_pk_fma_f32 v[224:225], v[12:13], v[162:163], v[224:225] op_sel_hi:[1,0,1]
	v_pk_fma_f32 v[226:227], v[14:15], v[162:163], v[226:227] op_sel_hi:[1,0,1]
	v_pk_fma_f32 v[228:229], v[16:17], v[162:163], v[228:229] op_sel_hi:[1,0,1]
	v_pk_fma_f32 v[230:231], v[18:19], v[162:163], v[230:231] op_sel_hi:[1,0,1]
	v_pk_fma_f32 v[232:233], v[20:21], v[162:163], v[232:233] op_sel_hi:[1,0,1]
	v_pk_fma_f32 v[234:235], v[22:23], v[162:163], v[234:235] op_sel_hi:[1,0,1]
	v_pk_fma_f32 v[236:237], v[24:25], v[162:163], v[236:237] op_sel_hi:[1,0,1]
	v_pk_fma_f32 v[182:183], v[26:27], v[162:163], v[182:183] op_sel_hi:[1,0,1]
	v_pk_fma_f32 v[184:185], v[28:29], v[162:163], v[184:185] op_sel_hi:[1,0,1]
	v_pk_fma_f32 v[208:209], v[30:31], v[162:163], v[208:209] op_sel_hi:[1,0,1]
	buffer_load_dwordx4 v[86:89], v210, s[48:51], 0 offen
	buffer_load_dwordx2 v[90:91], v210, s[48:51], 0 offen offset:16
	s_waitcnt vmcnt(39)
	v_cvt_scalef32_pk32_f32_fp6 v[0:31], v[68:73], 1.0
	v_lshrrev_b32_e32 v210, 16, v160
	v_mad_u32_u24 v210, v210, s12, v128
	v_pk_fma_f32 v[194:195], v[0:1], v[162:163], v[194:195] op_sel:[0,1,0] op_sel_hi:[1,1,1]
	v_pk_fma_f32 v[196:197], v[2:3], v[162:163], v[196:197] op_sel:[0,1,0] op_sel_hi:[1,1,1]
	v_pk_fma_f32 v[198:199], v[4:5], v[162:163], v[198:199] op_sel:[0,1,0] op_sel_hi:[1,1,1]
	v_pk_fma_f32 v[200:201], v[6:7], v[162:163], v[200:201] op_sel:[0,1,0] op_sel_hi:[1,1,1]
	v_pk_fma_f32 v[202:203], v[8:9], v[162:163], v[202:203] op_sel:[0,1,0] op_sel_hi:[1,1,1]
	v_pk_fma_f32 v[204:205], v[10:11], v[162:163], v[204:205] op_sel:[0,1,0] op_sel_hi:[1,1,1]
	v_pk_fma_f32 v[224:225], v[12:13], v[162:163], v[224:225] op_sel:[0,1,0] op_sel_hi:[1,1,1]
	v_pk_fma_f32 v[226:227], v[14:15], v[162:163], v[226:227] op_sel:[0,1,0] op_sel_hi:[1,1,1]
	v_pk_fma_f32 v[228:229], v[16:17], v[162:163], v[228:229] op_sel:[0,1,0] op_sel_hi:[1,1,1]
	v_pk_fma_f32 v[230:231], v[18:19], v[162:163], v[230:231] op_sel:[0,1,0] op_sel_hi:[1,1,1]
	v_pk_fma_f32 v[232:233], v[20:21], v[162:163], v[232:233] op_sel:[0,1,0] op_sel_hi:[1,1,1]
	v_pk_fma_f32 v[234:235], v[22:23], v[162:163], v[234:235] op_sel:[0,1,0] op_sel_hi:[1,1,1]
	v_pk_fma_f32 v[236:237], v[24:25], v[162:163], v[236:237] op_sel:[0,1,0] op_sel_hi:[1,1,1]
	v_pk_fma_f32 v[182:183], v[26:27], v[162:163], v[182:183] op_sel:[0,1,0] op_sel_hi:[1,1,1]
	v_pk_fma_f32 v[184:185], v[28:29], v[162:163], v[184:185] op_sel:[0,1,0] op_sel_hi:[1,1,1]
	v_pk_fma_f32 v[208:209], v[30:31], v[162:163], v[208:209] op_sel:[0,1,0] op_sel_hi:[1,1,1]
	buffer_load_dwordx4 v[68:71], v210, s[48:51], 0 offen
	buffer_load_dwordx2 v[72:73], v210, s[48:51], 0 offen offset:16
	s_waitcnt vmcnt(39)
; template <int CTRL> DI float dpp_add(float x) { return x + __uint_as_float(__builtin_amdgcn_update_dpp(0u, __float_as_uint(x), CTRL, 0xf, 0xf, true)); }
; DI void eseg_load(ESeg& r, __amdgpu_buffer_rsrc_t rs, int voff) { r.a = __builtin_amdgcn_raw_buffer_load_b128(rs, voff, 0, 0); r.b = __builtin_amdgcn_raw_buffer_load_b64(rs, voff + 16, 0, 0); }
; DI v32f eseg_unpack(const ESeg& r) { return __builtin_amdgcn_cvt_scalef32_pk32_f32_fp6((v6i){(int)r.a.x, (int)r.a.y, (int)r.a.z, (int)r.a.w, (int)r.b.x, (int)r.b.y}, 1.0f); }
; DI int id_of(const u32x4 (&d)[2], int r, unsigned mask = 0xffffu) { const unsigned w = d[r >> 3][(r >> 1) & 3]; return (r & 1) ? (int)((w >> 16) & mask) : (int)(w & mask); }
;     ...
; #pragma unroll
;         for (int r = 0; r < 16; ++r) {
;             const v32f rr = eseg_unpack(rw[r]); const f32x2 w2 = {wt[r], wt[r]};
; #pragma unroll
;             for (int j = 0; j < 16; ++j) fa[j] = __builtin_elementwise_fma((f32x2){rr[2 * j], rr[2 * j + 1]}, w2, fa[j]);
;             eseg_load(rw[r], VS, id_of(idn, r, mask) * ESEG + s24);
;             if (r & 1) __builtin_amdgcn_sched_barrier(0);
;         }
;         float f16[16], f8[8];
; #pragma unroll
;         for (int j = 0; j < 16; ++j) { const float lo = (j & 1) ? fa[j >> 1].y : fa[j >> 1].x, hi = (j & 1) ? fa[8 + (j >> 1)].y : fa[8 + (j >> 1)].x;
;             const auto a = __builtin_amdgcn_permlane32_swap(__float_as_uint(lo), __float_as_uint(hi), false, false); f16[j] = __uint_as_float(a[0]) + __uint_as_float(a[1]); }
; #pragma unroll
;         for (int j = 0; j < 8; ++j) { const auto a = __builtin_amdgcn_permlane16_swap(__float_as_uint(f16[j]), __float_as_uint(f16[j + 8]), false, false); f8[j] = __uint_as_float(a[0]) + __uint_as_float(a[1]); }
; #pragma unroll
;         for (int j = 0; j < 8; ++j) f8[j] = dpp_add<0x128>(f8[j]);
;         f32x4 z;
;         z.x = ALPHA * x1.x + g2.x * (b3 ? f8[4] : f8[0]); z.y = ALPHA * x1.y + g2.y * (b3 ? f8[5] : f8[1]); z.z = ALPHA * x1.z + g2.z * (b3 ? f8[6] : f8[2]); z.w = ALPHA * x1.w + g2.w * (b3 ? f8[7] : f8[3]);
;         if (!dry) *(f32x4*)xp = z;
;         if (tn >= nrows) break;
;         t = tn; idn[0] = idnn[0]; idn[1] = idnn[1];
	v_cvt_scalef32_pk32_f32_fp6 v[0:31], v[80:85], 1.0
	v_and_b32_e32 v210, 0xffff, v161
	v_mad_u32_u24 v210, v210, s12, v128
	v_pk_fma_f32 v[194:195], v[0:1], v[164:165], v[194:195] op_sel_hi:[1,0,1]
	v_pk_fma_f32 v[196:197], v[2:3], v[164:165], v[196:197] op_sel_hi:[1,0,1]
	v_pk_fma_f32 v[198:199], v[4:5], v[164:165], v[198:199] op_sel_hi:[1,0,1]
	v_pk_fma_f32 v[200:201], v[6:7], v[164:165], v[200:201] op_sel_hi:[1,0,1]
	v_pk_fma_f32 v[202:203], v[8:9], v[164:165], v[202:203] op_sel_hi:[1,0,1]
	v_pk_fma_f32 v[204:205], v[10:11], v[164:165], v[204:205] op_sel_hi:[1,0,1]
	v_pk_fma_f32 v[224:225], v[12:13], v[164:165], v[224:225] op_sel_hi:[1,0,1]
	v_pk_fma_f32 v[226:227], v[14:15], v[164:165], v[226:227] op_sel_hi:[1,0,1]
	v_pk_fma_f32 v[228:229], v[16:17], v[164:165], v[228:229] op_sel_hi:[1,0,1]
	v_pk_fma_f32 v[230:231], v[18:19], v[164:165], v[230:231] op_sel_hi:[1,0,1]
	v_pk_fma_f32 v[232:233], v[20:21], v[164:165], v[232:233] op_sel_hi:[1,0,1]
	v_pk_fma_f32 v[234:235], v[22:23], v[164:165], v[234:235] op_sel_hi:[1,0,1]
	v_pk_fma_f32 v[236:237], v[24:25], v[164:165], v[236:237] op_sel_hi:[1,0,1]
	v_pk_fma_f32 v[182:183], v[26:27], v[164:165], v[182:183] op_sel_hi:[1,0,1]
	v_pk_fma_f32 v[184:185], v[28:29], v[164:165], v[184:185] op_sel_hi:[1,0,1]
	v_pk_fma_f32 v[208:209], v[30:31], v[164:165], v[208:209] op_sel_hi:[1,0,1]
	buffer_load_dwordx4 v[80:83], v210, s[48:51], 0 offen
	buffer_load_dwordx2 v[84:85], v210, s[48:51], 0 offen offset:16
	s_waitcnt vmcnt(39)
	v_cvt_scalef32_pk32_f32_fp6 v[0:31], v[74:79], 1.0
	v_lshrrev_b32_e32 v210, 16, v161
	v_mad_u32_u24 v210, v210, s12, v128
	v_pk_fma_f32 v[194:195], v[0:1], v[164:165], v[194:195] op_sel:[0,1,0] op_sel_hi:[1,1,1]
	v_pk_fma_f32 v[196:197], v[2:3], v[164:165], v[196:197] op_sel:[0,1,0] op_sel_hi:[1,1,1]
	v_pk_fma_f32 v[228:229], v[16:17], v[164:165], v[228:229] op_sel:[0,1,0] op_sel_hi:[1,1,1]
	v_pk_fma_f32 v[16:17], v[20:21], v[164:165], v[232:233] op_sel:[0,1,0] op_sel_hi:[1,1,1]
	v_pk_fma_f32 v[198:199], v[4:5], v[164:165], v[198:199] op_sel:[0,1,0] op_sel_hi:[1,1,1]
	v_pk_fma_f32 v[200:201], v[6:7], v[164:165], v[200:201] op_sel:[0,1,0] op_sel_hi:[1,1,1]
	v_pk_fma_f32 v[202:203], v[8:9], v[164:165], v[202:203] op_sel:[0,1,0] op_sel_hi:[1,1,1]
	v_pk_fma_f32 v[8:9], v[10:11], v[164:165], v[204:205] op_sel:[0,1,0] op_sel_hi:[1,1,1]
	v_pk_fma_f32 v[4:5], v[12:13], v[164:165], v[224:225] op_sel:[0,1,0] op_sel_hi:[1,1,1]
	v_pk_fma_f32 v[0:1], v[14:15], v[164:165], v[226:227] op_sel:[0,1,0] op_sel_hi:[1,1,1]
	v_pk_fma_f32 v[18:19], v[18:19], v[164:165], v[230:231] op_sel:[0,1,0] op_sel_hi:[1,1,1]
	v_pk_fma_f32 v[14:15], v[22:23], v[164:165], v[234:235] op_sel:[0,1,0] op_sel_hi:[1,1,1]
	v_pk_fma_f32 v[12:13], v[24:25], v[164:165], v[236:237] op_sel:[0,1,0] op_sel_hi:[1,1,1]
	v_pk_fma_f32 v[10:11], v[26:27], v[164:165], v[182:183] op_sel:[0,1,0] op_sel_hi:[1,1,1]
	v_pk_fma_f32 v[6:7], v[28:29], v[164:165], v[184:185] op_sel:[0,1,0] op_sel_hi:[1,1,1]
	v_pk_fma_f32 v[2:3], v[30:31], v[164:165], v[208:209] op_sel:[0,1,0] op_sel_hi:[1,1,1]
	buffer_load_dwordx4 v[74:77], v210, s[48:51], 0 offen
	buffer_load_dwordx2 v[78:79], v210, s[48:51], 0 offen offset:16
	v_permlane32_swap_b32_e32 v194, v228
	v_permlane32_swap_b32_e32 v195, v229
	v_permlane32_swap_b32_e32 v196, v18
	v_permlane32_swap_b32_e32 v197, v19
	v_permlane32_swap_b32_e32 v198, v16
	v_permlane32_swap_b32_e32 v199, v17
	v_permlane32_swap_b32_e32 v200, v14
	v_permlane32_swap_b32_e32 v201, v15
	v_permlane32_swap_b32_e32 v202, v12
	v_permlane32_swap_b32_e32 v203, v13
	v_permlane32_swap_b32_e32 v8, v10
	v_permlane32_swap_b32_e32 v9, v11
	v_permlane32_swap_b32_e32 v4, v6
	v_permlane32_swap_b32_e32 v5, v7
	v_permlane32_swap_b32_e32 v0, v2
	v_permlane32_swap_b32_e32 v1, v3
	v_add_f32_e32 v20, v194, v228
	v_add_f32_e32 v21, v195, v229
	v_add_f32_e32 v18, v196, v18
	v_add_f32_e32 v19, v197, v19
	v_add_f32_e32 v16, v198, v16
	v_add_f32_e32 v17, v199, v17
	v_add_f32_e32 v14, v200, v14
	v_add_f32_e32 v15, v201, v15
	v_add_f32_e32 v12, v202, v12
	v_add_f32_e32 v13, v203, v13
	v_add_f32_e32 v8, v8, v10
	v_add_f32_e32 v9, v9, v11
	v_add_f32_e32 v4, v4, v6
	v_add_f32_e32 v5, v5, v7
	v_add_f32_e32 v0, v0, v2
	v_add_f32_e32 v1, v1, v3
	v_permlane16_swap_b32_e32 v20, v12
	v_permlane16_swap_b32_e32 v21, v13
	v_permlane16_swap_b32_e32 v18, v8
	v_permlane16_swap_b32_e32 v19, v9
	v_permlane16_swap_b32_e32 v16, v4
	v_permlane16_swap_b32_e32 v17, v5
	v_permlane16_swap_b32_e32 v14, v0
	v_permlane16_swap_b32_e32 v15, v1
	v_pk_add_f32 v[2:3], v[20:21], v[12:13]
	v_pk_add_f32 v[4:5], v[16:17], v[4:5]
	v_pk_add_f32 v[8:9], v[18:19], v[8:9]
	v_pk_add_f32 v[0:1], v[14:15], v[0:1]
	v_mov_b32_dpp v6, v2 row_ror:8 row_mask:0xf bank_mask:0xf bound_ctrl:1
	v_mov_b32_dpp v7, v3 row_ror:8 row_mask:0xf bank_mask:0xf bound_ctrl:1
	v_mov_b32_dpp v10, v4 row_ror:8 row_mask:0xf bank_mask:0xf bound_ctrl:1
	v_mov_b32_dpp v11, v5 row_ror:8 row_mask:0xf bank_mask:0xf bound_ctrl:1
	v_mov_b32_dpp v12, v8 row_ror:8 row_mask:0xf bank_mask:0xf bound_ctrl:1
	v_mov_b32_dpp v13, v9 row_ror:8 row_mask:0xf bank_mask:0xf bound_ctrl:1
	v_mov_b32_dpp v14, v0 row_ror:8 row_mask:0xf bank_mask:0xf bound_ctrl:1
	v_mov_b32_dpp v15, v1 row_ror:8 row_mask:0xf bank_mask:0xf bound_ctrl:1
	v_pk_add_f32 v[8:9], v[8:9], v[12:13]
	v_pk_add_f32 v[2:3], v[2:3], v[6:7]
	v_pk_add_f32 v[4:5], v[4:5], v[10:11]
	v_pk_add_f32 v[0:1], v[0:1], v[14:15]
	v_cndmask_b32_e32 v3, v5, v3, vcc
	v_cndmask_b32_e32 v1, v1, v9, vcc
	v_cndmask_b32_e32 v0, v0, v8, vcc
	v_cndmask_b32_e32 v2, v4, v2, vcc
	s_waitcnt vmcnt(32)
	v_pk_mul_f32 v[0:1], v[172:173], v[0:1]
	v_pk_mul_f32 v[4:5], v[170:171], v[2:3]
	v_mov_b64_e32 v[158:159], v[130:131]
	v_mov_b64_e32 v[160:161], v[132:133]
	v_pk_fma_f32 v[2:3], v[168:169], s[14:15], v[0:1] op_sel_hi:[1,0,1]
	v_pk_fma_f32 v[0:1], v[166:167], s[14:15], v[4:5] op_sel_hi:[1,0,1]
	v_mov_b64_e32 v[186:187], v[134:135]
	v_mov_b64_e32 v[188:189], v[136:137]
	global_store_dwordx4 v[220:221], v[0:3], off
	v_lshl_add_u64 v[220:221], v[220:221], 0, s[8:9]
	s_or_b64 s[10:11], s[36:37], s[10:11]
	v_mov_b64_e32 v[162:163], v[138:139]
	v_mov_b64_e32 v[164:165], v[140:141]
	v_mov_b64_e32 v[174:175], v[142:143]
	v_mov_b64_e32 v[176:177], v[144:145]
	v_mov_b64_e32 v[190:191], v[146:147]
	v_mov_b64_e32 v[192:193], v[148:149]
	v_mov_b64_e32 v[178:179], v[150:151]
	v_mov_b64_e32 v[180:181], v[152:153]
	v_mov_b32_e32 v0, v250
	s_andn2_b64 exec, exec, s[10:11]
	s_cbranch_execnz .LBB0_1095
